# lean G1 epilogue addressing; dil attention items permuted so neighbouring key blocks run on one XCD
# speedup vs baseline: 1.0195x; 1.0056x over previous
; DI void dil_store(const DilPre& P, bf16x8 (&qf)[4], ldsp lds, const bf16_t* proj, const float* rope, int item, int tid, int wid, int lane) {
;     const DilItem d = dil_decode(item);
;     const ldsp Kb = lds, Vb = lds + 256 * DIL_KS;
;     const int li = lane & 15, quad = lane >> 4;
;     const int tq = (128 * d.jb + 16 * wid + li) * d.r + d.ph;
;     float4 qcs[4], kcs[4];
;     {
;         const bf16_t* qsrc = proj + (d.rowbase + tq) * DIL_N + d.qcol + quad * 8;
; #pragma unroll
;         for (int ks = 0; ks < 4; ++ks) qf[ks] = *(const bf16x8*)(qsrc + ks * 32);
;         const float4* rp = (const float4*)(rope + (size_t)tq * 32 + 16 * (quad & 1));
; #pragma unroll
;         for (int jj = 0; jj < 4; ++jj) qcs[jj] = rp[jj];
;     }
;     const int prow = tid >> 1, pc = tid & 1, psp = d.s_k0 + prow;
;     u32x4 kp1 = (u32x4){0u, 0u, 0u, 0u}, kp2 = kp1;
;     {
;         const int tok = (psp >= 0 ? psp : 0) * d.r + d.ph;
;         const bf16_t* ksrc = proj + (d.rowbase + tok) * DIL_N + d.qcol + 768 + 8 * pc;
;         kp1 = *(const u32x4*)ksrc; kp2 = *(const u32x4*)(ksrc + 16);
;         const float4* rp = (const float4*)(rope + (size_t)tok * 32 + 16 * pc);
; #pragma unroll
;         for (int jj = 0; jj < 4; ++jj) kcs[jj] = rp[jj];
;     }
.LBB0_331:
	s_and_b32 s98, s15, 7
	s_lshl_b32 s98, s98, 5
	s_bfe_u32 s99, s15, 0x10007
	s_lshl_b32 s99, s99, 4
	s_or_b32 s98, s98, s99
	s_bfe_u32 s99, s15, 0x40003
	s_or_b32 s98, s98, s99
	s_and_b32 s99, s15, 0xffffff00
	s_or_b32 s98, s98, s99
	s_cmpk_lt_u32 s15, 0x100
	s_cselect_b32 s98, s15, s98
	s_ashr_i32 s19, s98, 4
	s_mul_hi_i32 s22, s19, 0x55555556
	s_lshr_b32 s23, s22, 31
	s_add_i32 s22, s22, s23
	s_mul_i32 s23, s22, 3
	s_sub_i32 s36, s19, s23
	s_mul_hi_i32 s23, s22, 0x2aaaaaab
	s_lshr_b32 s26, s23, 31
	s_add_i32 s23, s23, s26
	s_mul_i32 s23, s23, 6
	s_mul_hi_i32 s19, s19, 0x38e38e39
	s_lshr_b32 s14, s15, 8
	s_sub_i32 s58, s22, s23
	s_lshr_b32 s22, s19, 31
	s_ashr_i32 s19, s19, 2
	s_lshl_b32 s37, s36, 1
	s_add_i32 s14, s14, s98
	s_add_i32 s22, s19, s22
	s_lshr_b32 s19, 16, s37
	v_mov_b32_e32 v135, v32
	s_and_b32 s14, s14, 15
	s_sub_i32 s23, 4, s37
	s_add_i32 s19, s19, -1
	s_lshr_b32 s59, s14, s23
	v_readfirstlane_b32 s17, v135
	s_and_b32 s19, s19, s14
	s_ashr_i32 s23, s22, 31
	s_mul_i32 s14, s36, 0x900
	s_lshl_b32 s60, s58, 7
	s_lshl_b64 s[62:63], s[22:23], 11
	s_add_i32 s22, s60, s14
	s_ashr_i32 s14, s17, 2
	s_lshl_b32 s61, s19, 7
	s_and_b32 s65, s14, -16
	v_and_b32_e32 v136, 15, v135
	s_add_i32 s14, s65, s61
	v_or_b32_e32 v13, s14, v136
	v_lshlrev_b32_e32 v13, s37, v13
	v_add_u32_e32 v14, s59, v13
	v_ashrrev_i32_e32 v15, 31, v14
	v_lshl_add_u64 v[62:63], s[62:63], 0, v[14:15]
	v_lshlrev_b64 v[62:63], 14, v[62:63]
	s_ashr_i32 s23, s22, 31
	v_readlane_b32 s26, v254, 58
	v_lshl_add_u64 v[62:63], s[42:43], 0, v[62:63]
	s_lshl_b64 s[22:23], s[22:23], 1
	v_lshlrev_b64 v[14:15], 7, v[14:15]
	v_readlane_b32 s27, v254, 59
	v_and_b32_e32 v13, 16, v135
	v_lshl_add_u64 v[62:63], v[62:63], 0, s[22:23]
	v_and_b32_e32 v118, 48, v135
	v_mov_b32_e32 v119, v12
	v_lshl_add_u64 v[14:15], s[26:27], 0, v[14:15]
	v_lshlrev_b32_e32 v78, 2, v13
	v_mov_b32_e32 v79, v12
	v_lshl_add_u64 v[70:71], v[62:63], 0, v[118:119]
	v_lshl_add_u64 v[14:15], v[14:15], 0, v[78:79]
	s_add_i32 s14, s61, 0xffffff80
	v_ashrrev_i32_e32 v33, 1, v135
	global_load_dwordx4 v[74:77], v[70:71], off
	global_load_dwordx4 v[62:65], v[70:71], off offset:64
	global_load_dwordx4 v[66:69], v[70:71], off offset:128
	s_nop 0
	global_load_dwordx4 v[70:73], v[70:71], off offset:192
	s_nop 0
	global_load_dwordx4 v[78:81], v[14:15], off offset:48
	global_load_dwordx4 v[82:85], v[14:15], off offset:32
	global_load_dwordx4 v[86:89], v[14:15], off offset:16
	global_load_dwordx4 v[90:93], v[14:15], off
	v_add_u32_e32 v14, s14, v33
	v_cmp_lt_i32_e32 vcc, -1, v14
	v_and_b32_e32 v13, 1, v135
	s_sub_i32 s64, 0x7f, s61
	v_cndmask_b32_e32 v14, 0, v14, vcc
	v_lshlrev_b32_e32 v14, s37, v14
	v_add_u32_e32 v94, s59, v14
	v_ashrrev_i32_e32 v95, 31, v94
	v_lshl_add_u64 v[14:15], s[62:63], 0, v[94:95]
	v_lshlrev_b64 v[14:15], 14, v[14:15]
	v_lshl_add_u64 v[14:15], s[42:43], 0, v[14:15]
	v_lshl_add_u64 v[96:97], v[14:15], 0, s[22:23]
	v_lshlrev_b32_e32 v14, 4, v13
	v_mov_b32_e32 v15, v12
	v_lshl_add_u64 v[96:97], v[96:97], 0, v[14:15]
	v_lshlrev_b64 v[94:95], 7, v[94:95]
	global_load_dwordx4 v[98:101], v[96:97], off offset:1536
	global_load_dwordx4 v[102:105], v[96:97], off offset:1568
	v_lshl_add_u64 v[94:95], s[26:27], 0, v[94:95]
	v_lshlrev_b32_e32 v96, 6, v13
	v_mov_b32_e32 v97, v12
	v_lshl_add_u64 v[114:115], v[94:95], 0, v[96:97]
	global_load_dwordx4 v[94:97], v[114:115], off offset:48
	global_load_dwordx4 v[106:109], v[114:115], off offset:32
	global_load_dwordx4 v[110:113], v[114:115], off offset:16
	s_nop 0
	global_load_dwordx4 v[114:117], v[114:115], off
	v_mul_hi_i32 v13, v135, s68
	v_lshrrev_b32_e32 v15, 31, v13
	v_ashrrev_i32_e32 v13, 1, v13
	v_add_u32_e32 v139, v13, v15
	v_cmp_lt_i32_e64 s[38:39], s64, v139
	s_and_saveexec_b64 s[22:23], s[38:39]
	s_cbranch_execz .LBB0_333
	s_mov_b32 s14, 0xffffff4
	v_mul_lo_u32 v13, v139, s14
	s_movk_i32 s14, 0x110
	v_mul_lo_u32 v15, v139, s14
	v_add_lshl_u32 v13, v13, v135, 4
	v_add3_u32 v13, 0, v15, v13
	s_waitcnt vmcnt(14) lgkmcnt(0)
	ds_write_b128 v13, v[4:7] offset:64

; DI void dil_load(DilPre& P, const bf16_t* proj, int item, int tid, int wid, int lane) {
;     const DilItem d = dil_decode(item);
;     const int kcol = d.qcol + 768, vcol = d.qcol + 1536;
;     const u32x4 z = (u32x4){0u, 0u, 0u, 0u};
; #pragma unroll
;     for (int i = 0; i < 6; ++i) {
;         const int e = tid + i * 512, row = e / 12, ch = 4 + (e - row * 12), sp = d.s_k0 + row;
;         P.kc[i] = z;
;         if (sp >= 0) P.kc[i] = *(const u32x4*)(proj + (d.rowbase + sp * d.r + d.ph) * DIL_N + kcol + ch * 8);
.LBB0_361:
	s_or_b64 exec, exec, s[26:27]
	v_and_b32_e32 v33, 64, v233
	v_xor_b32_e32 v14, 32, v233
	v_add_u32_e32 v33, 64, v33
	v_cmp_lt_i32_e32 vcc, v14, v33
	s_add_i32 s14, s15, s10
	s_cmpk_gt_i32 s14, 0x8ff
	v_cndmask_b32_e32 v14, v233, v14, vcc
	v_lshlrev_b32_e32 v119, 2, v14
	s_waitcnt vmcnt(0)
	ds_bpermute_b32 v99, v119, v74
	ds_bpermute_b32 v98, v119, v75
	ds_bpermute_b32 v97, v119, v76
	ds_bpermute_b32 v96, v119, v77
	s_cselect_b64 s[56:57], -1, 0
	s_and_b64 vcc, exec, s[56:57]
	s_waitcnt lgkmcnt(0)
	s_barrier
	s_cbranch_vccnz .LBB0_391
	s_and_b32 s99, s14, 7
	s_lshl_b32 s99, s99, 5
	s_bfe_u32 s100, s14, 0x10007
	s_lshl_b32 s100, s100, 4
	s_or_b32 s99, s99, s100
	s_bfe_u32 s100, s14, 0x40003
	s_or_b32 s99, s99, s100
	s_and_b32 s100, s14, 0xffffff00
	s_or_b32 s99, s99, s100
	s_lshr_b32 s22, s14, 8
	s_add_i32 s22, s22, s99
	s_and_b32 s23, s22, 15
	s_ashr_i32 s22, s99, 4
	s_mul_hi_i32 s26, s22, 0x55555556
	s_lshr_b32 s27, s26, 31
	s_add_i32 s26, s26, s27
	s_mul_i32 s27, s26, 3
	s_sub_i32 s30, s22, s27
	s_mul_hi_i32 s27, s26, 0x2aaaaaab
	s_lshr_b32 s31, s27, 31
	s_add_i32 s27, s27, s31
	s_mul_i32 s27, s27, 6
	s_mul_hi_i32 s22, s22, 0x38e38e39
	s_sub_i32 s31, s26, s27
	s_lshr_b32 s26, s22, 31
	s_ashr_i32 s22, s22, 2
	s_lshl_b32 s38, s30, 1
	s_add_i32 s22, s22, s26
	s_lshr_b32 s26, 16, s38
	s_sub_i32 s27, 4, s38
	s_add_i32 s26, s26, -1
	s_lshr_b32 s35, s23, s27
	s_and_b32 s34, s26, s23
	s_ashr_i32 s23, s22, 31
	s_lshl_b64 s[26:27], s[22:23], 11
	s_mulk_i32 s30, 0x900
	s_lshl_b32 s22, s31, 7
	s_add_i32 s22, s22, s30
	s_lshl_b32 s34, s34, 7
	s_ashr_i32 s23, s22, 31
	s_addk_i32 s34, 0xff80
	s_or_b32 s26, s26, s35
	s_lshl_b64 s[22:23], s[22:23], 1
	v_mov_b32_e32 v2, v12
	v_mov_b32_e32 v3, v12
	s_add_u32 s30, s42, s22
	v_add_u32_e32 v8, s34, v139
	v_mov_b32_e32 v0, v12
	v_mov_b32_e32 v1, v12
	v_mov_b64_e32 v[6:7], v[2:3]
	s_addc_u32 s31, s43, s23
	v_cmp_lt_i32_e32 vcc, -1, v8
	v_mov_b64_e32 v[4:5], v[0:1]
	s_and_saveexec_b64 s[22:23], vcc
	s_cbranch_execz .LBB0_364
	s_mov_b32 s35, 0x1ffffff4
	v_lshlrev_b32_e32 v4, s38, v8
	v_mov_b32_e32 v5, v12
	v_mul_lo_u32 v6, v139, s35
	v_lshl_add_u64 v[4:5], s[26:27], 0, v[4:5]
	v_lshlrev_b64 v[4:5], 14, v[4:5]
	v_add_lshl_u32 v6, v6, v135, 3
	v_lshl_add_u64 v[4:5], s[30:31], 0, v[4:5]
	v_ashrrev_i32_e32 v7, 31, v6
	v_lshl_add_u64 v[4:5], v[6:7], 1, v[4:5]
	global_load_dwordx4 v[4:7], v[4:5], off offset:1600

; #define PG8_STAGE(bufoff, gbase, voff) do { _Pragma("unroll") for (int _i = 0; _i < 2; ++_i) \
;         __builtin_amdgcn_global_load_lds((const unsigned*)((const char*)(gbase) + (voff)[_i]), (LAS unsigned*)(lds + (bufoff) + ldsw + _i * 8192), 16, 0, 0); } while (0)
; #define PG8_WAIT_V(n) asm volatile("s_waitcnt vmcnt(" #n ")" ::: "memory")
; #define PG8_BAR __builtin_amdgcn_s_barrier()
;     DI void operator()(const f32x4 (&acc)[2][2][4][2], const Unit& u, int wr, int wc, int fr, int fq) const {
;         const int row0 = u.pm * BM + wr * 64 + fr; const int col0 = u.pn * BM + wc * 32 + 8 * fq;
; template <class Epi, class Sched>
; DI void gemm_phase(ldsp lds, const Gemm g, const Sched& S, const Epi& E, const int tid) {
;     ...
;     const char* cA = (const char*)g.A + (size_t)cur.pm * tstep; const char* cB = (const char*)g.Bt + (size_t)cur.pn * tstep;
;     PG8_STAGE(PG8_SB(0, 0), cB, voffB); PG8_STAGE(PG8_SA(0, 0), cA, voffA); PG8_STAGE(PG8_SB(0, 1), cB + hstep, voffB); PG8_STAGE(PG8_SA(0, 1), cA + hstep, voffA);
;     if (wr == 1) PG8_BAR;
;     PG8_WAIT_V(4); PG8_BAR;
;     PG8_STAGE(PG8_SB(1, 0), cB + kstep, voffB); PG8_STAGE(PG8_SA(1, 0), cA + kstep, voffA); PG8_STAGE(PG8_SB(1, 1), cB + hstep + kstep, voffB);
;     PG8_WAIT_V(6); PG8_BAR;
.LBB0_659:
	s_sext_i32_i16 s64, s26
	v_readlane_b32 s26, v255, 9
	s_lshl_b32 s26, s26, 27
	s_and_b32 s38, s26, 0x8000000
	s_and_b64 s[26:27], s[42:43], exec
	s_cselect_b32 s26, 0, s38
	s_lshl_b32 s26, s26, 1
	v_readlane_b32 s38, v251, 15
	v_readlane_b32 s39, v251, 16
	s_add_u32 s26, s38, s26
	v_lshrrev_b32_e32 v16, 1, v32
	s_addc_u32 s27, s39, 0
	v_and_b32_e32 v16, 24, v16
	s_lshl_b32 s36, s36, 5
	v_lshlrev_b32_e32 v17, 1, v16
	v_lshlrev_b32_e32 v18, 2, v155
	s_and_b32 s38, s36, 0x60
	s_add_i32 m0, s31, 0x18000
	v_lshl_add_u64 v[6:7], v[6:7], 0, s[96:97]
	v_lshl_or_b32 v13, s37, 6, v155
	v_lshl_or_b32 v17, v155, 6, v17
	s_lshl_b32 s37, s37, 13
	v_and_b32_e32 v18, 32, v18
	s_lshl_b32 s36, s38, 7
	s_waitcnt vmcnt(4)
	s_barrier
	global_load_lds_dwordx4 v[6:7], off
	v_lshl_add_u64 v[4:5], v[4:5], 0, s[96:97]
	s_add_i32 m0, s31, 0x1a000
	s_add_i32 s62, s31, 0x8000
	s_add_i32 s63, s31, 0xa000
	v_bitop3_b32 v33, s36, v17, v18 bitop3:0xf6
	global_load_lds_dwordx4 v[4:5], off
	v_lshl_add_u64 v[2:3], v[2:3], 0, s[96:97]
	s_mov_b32 m0, s62
	s_add_u32 s36, s48, 0x40080
	v_bitop3_b32 v19, v17, s37, v18 bitop3:0xde
	global_load_lds_dwordx4 v[2:3], off
	v_lshl_add_u64 v[0:1], v[0:1], 0, s[96:97]
	s_mov_b32 m0, s63
	s_addc_u32 s37, s49, 0
	global_load_lds_dwordx4 v[0:1], off
	s_add_i32 m0, s31, 0x1c000
	v_lshl_add_u64 v[0:1], s[36:37], 0, v[136:137]
	global_load_lds_dwordx4 v[0:1], off
	v_lshl_add_u64 v[0:1], s[36:37], 0, v[30:31]
	s_add_i32 m0, s31, 0x1e000
	s_mov_b32 s61, 0
	global_load_lds_dwordx4 v[0:1], off
	v_lshlrev_b32_e32 v0, 14, v14
	v_and_b32_e32 v0, 0xffff8000, v0
	v_lshl_add_u32 v0, v11, 11, v0
	v_and_b32_e32 v1, 1, v14
	v_lshl_or_b32 v0, v1, 6, v0
	v_lshl_add_u32 v140, v15, 1, v0
	v_lshlrev_b32_e32 v0, 14, v8
	v_and_b32_e32 v0, 0xffff8000, v0
	s_waitcnt vmcnt(6)
	v_lshl_add_u32 v0, v9, 11, v0
	v_and_b32_e32 v1, 1, v8
	v_lshl_or_b32 v0, v1, 6, v0
	v_or_b32_e32 v144, s38, v16
	v_mov_b32_e32 v141, v12
	v_lshl_add_u32 v142, v10, 1, v0
	v_mov_b32_e32 v143, v12
	v_add_u32_e32 v145, 0, v19
	s_barrier
	v_mul_lo_u32 v224, v13, s14
	v_add_lshl_u32 v224, v224, v144, 1
	s_lshl_b32 s100, s14, 5

; #define PG8_STAGE(bufoff, gbase, voff) do { _Pragma("unroll") for (int _i = 0; _i < 2; ++_i) \
;         __builtin_amdgcn_global_load_lds((const unsigned*)((const char*)(gbase) + (voff)[_i]), (LAS unsigned*)(lds + (bufoff) + ldsw + _i * 8192), 16, 0, 0); } while (0)
; #define PG8_LDA(dst, b, h) do { _Pragma("unroll") for (int m = 0; m < 4; ++m) _Pragma("unroll") for (int k = 0; k < 2; ++k) dst[m][k] = *(const LAS bf16x8*)(lds + PG8_SA(b, h) + aoff + m * 2048 + k * 1024); } while (0)
; #define PG8_LDB(dst, b, h) do { _Pragma("unroll") for (int n = 0; n < 2; ++n) _Pragma("unroll") for (int k = 0; k < 2; ++k) dst[n][k] = *(const LAS bf16x8*)(lds + PG8_SB(b, h) + boff + n * 2048 + k * 1024); } while (0)
; #define PG8_MMA(ai, bj, At, Bt) do { __builtin_amdgcn_s_setprio(1); _Pragma("unroll") for (int m = 0; m < 4; ++m) _Pragma("unroll") for (int n = 0; n < 2; ++n) _Pragma("unroll") for (int k = 0; k < 2; ++k) \
;         acc[ai][bj][m][n] = __builtin_amdgcn_mfma_f32_16x16x32_bf16(Bt[n][k], At[m][k], acc[ai][bj][m][n], 0, 0, 0); __builtin_amdgcn_s_setprio(0); } while (0)
; #define PG8_WAIT_L(n) asm volatile("s_waitcnt lgkmcnt(" #n ")" ::: "memory")
; #define PG8_BAR __builtin_amdgcn_s_barrier()
; #define PG8_SCHED __builtin_amdgcn_sched_barrier(0)
; template <class Epi, class Sched>
; DI void gemm_phase(ldsp lds, const Gemm g, const Sched& S, const Epi& E, const int tid) {
;     ...
;             PG8_LDB(B0, 0, 0); PG8_SCHED; PG8_LDA(At, 0, 0); PG8_STAGE(PG8_SA(1, 1), a1 + hstep, voffA);
;             PG8_WAIT_L(8); PG8_BAR; PG8_WAIT_L(0); PG8_MMA(0, 0, At, B0); PG8_BAR; PG8_SCHED;
;             PG8_LDB(B1, 0, 1); PG8_STAGE(PG8_SB(0, 0), b2, voffB);
;             PG8_BAR; PG8_WAIT_L(0); PG8_MMA(0, 1, At, B1); PG8_BAR;
;             PG8_LDA(At, 0, 1); PG8_STAGE(PG8_SA(0, 0), a2, voffA);
;             PG8_BAR; PG8_WAIT_L(0); PG8_MMA(1, 0, At, B0); PG8_BAR; PG8_SCHED;
.LBB0_663:
	s_add_u32 s48, s46, 0xfffc0080
	s_addc_u32 s49, s47, -1
	s_add_i32 s72, 0, 0x10000
	v_add_u32_e32 v156, s72, v33
	ds_read_b128 v[146:149], v156
	ds_read_b128 v[150:153], v156 offset:1024
	ds_read_b128 v[162:165], v156 offset:2048
	ds_read_b128 v[166:169], v156 offset:3072
	s_cmp_eq_u32 s69, 12
	s_cselect_b32 s51, s41, s49
	s_cselect_b32 s50, s65, s48
	s_cselect_b32 s49, s37, s68
	s_cselect_b32 s48, s66, s67
	v_lshl_add_u64 v[158:159], s[46:47], 0, v[140:141]
	s_add_i32 m0, s31, 0xc000
	ds_read_b128 v[170:173], v145
	ds_read_b128 v[174:177], v145 offset:1024
	ds_read_b128 v[178:181], v145 offset:2048
	ds_read_b128 v[182:185], v145 offset:3072
	ds_read_b128 v[186:189], v145 offset:4096
	ds_read_b128 v[190:193], v145 offset:5120
	ds_read_b128 v[194:197], v145 offset:6144
	ds_read_b128 v[198:201], v145 offset:7168
	global_load_lds_dwordx4 v[158:159], off
	v_lshl_add_u64 v[158:159], s[46:47], 0, v[142:143]
	s_add_i32 m0, s31, 0xe000
	s_nop 0
	global_load_lds_dwordx4 v[158:159], off
	s_waitcnt lgkmcnt(8)
	s_barrier
	s_waitcnt lgkmcnt(0)
	s_setprio 1
	s_waitcnt lgkmcnt(0)
	v_mfma_f32_16x16x32_bf16 v[130:133], v[146:149], v[170:173], v[130:133]
	v_mfma_f32_16x16x32_bf16 v[126:129], v[162:165], v[170:173], v[126:129]
	v_mfma_f32_16x16x32_bf16 v[122:125], v[146:149], v[178:181], v[122:125]
	v_mfma_f32_16x16x32_bf16 v[118:121], v[162:165], v[178:181], v[118:121]
	v_mfma_f32_16x16x32_bf16 v[106:109], v[146:149], v[186:189], v[106:109]
	v_mfma_f32_16x16x32_bf16 v[102:105], v[162:165], v[186:189], v[102:105]
	v_mfma_f32_16x16x32_bf16 v[90:93], v[146:149], v[194:197], v[90:93]
	v_mfma_f32_16x16x32_bf16 v[86:89], v[162:165], v[194:197], v[86:89]
	v_mfma_f32_16x16x32_bf16 v[130:133], v[150:153], v[174:177], v[130:133]
	v_mfma_f32_16x16x32_bf16 v[126:129], v[166:169], v[174:177], v[126:129]
	v_mfma_f32_16x16x32_bf16 v[122:125], v[150:153], v[182:185], v[122:125]
	v_mfma_f32_16x16x32_bf16 v[118:121], v[166:169], v[182:185], v[118:121]
	v_mfma_f32_16x16x32_bf16 v[106:109], v[150:153], v[190:193], v[106:109]
	v_mfma_f32_16x16x32_bf16 v[102:105], v[166:169], v[190:193], v[102:105]
	v_mfma_f32_16x16x32_bf16 v[90:93], v[150:153], v[198:201], v[90:93]
	v_mfma_f32_16x16x32_bf16 v[86:89], v[166:169], v[198:201], v[86:89]
	s_setprio 0
	s_barrier
	s_add_i32 s74, 0, 0x14000
	s_add_i32 s72, s72, s35
	v_add_u32_e32 v156, s74, v33
	v_lshl_add_u64 v[158:159], s[48:49], 0, v[136:137]
	s_mov_b32 m0, s72
	ds_read_b128 v[202:205], v156
	ds_read_b128 v[206:209], v156 offset:1024
	ds_read_b128 v[210:213], v156 offset:2048
	ds_read_b128 v[214:217], v156 offset:3072
	global_load_lds_dwordx4 v[158:159], off
	v_lshl_add_u64 v[160:161], s[48:49], 0, v[30:31]
	s_add_i32 m0, s72, 0x2000
	s_nop 0
	global_load_lds_dwordx4 v[160:161], off
	s_barrier
	s_waitcnt lgkmcnt(0)
	s_setprio 1
	s_waitcnt lgkmcnt(0)
	v_mfma_f32_16x16x32_bf16 v[114:117], v[202:205], v[170:173], v[114:117]
	v_mfma_f32_16x16x32_bf16 v[110:113], v[210:213], v[170:173], v[110:113]
	v_mfma_f32_16x16x32_bf16 v[98:101], v[202:205], v[178:181], v[98:101]
	v_mfma_f32_16x16x32_bf16 v[94:97], v[210:213], v[178:181], v[94:97]
	v_mfma_f32_16x16x32_bf16 v[82:85], v[202:205], v[186:189], v[82:85]
	v_mfma_f32_16x16x32_bf16 v[78:81], v[210:213], v[186:189], v[78:81]
	v_mfma_f32_16x16x32_bf16 v[74:77], v[202:205], v[194:197], v[74:77]
	v_mfma_f32_16x16x32_bf16 v[70:73], v[210:213], v[194:197], v[70:73]
	v_mfma_f32_16x16x32_bf16 v[114:117], v[206:209], v[174:177], v[114:117]
	v_mfma_f32_16x16x32_bf16 v[110:113], v[214:217], v[174:177], v[110:113]
	v_mfma_f32_16x16x32_bf16 v[98:101], v[206:209], v[182:185], v[98:101]
	v_mfma_f32_16x16x32_bf16 v[94:97], v[214:217], v[182:185], v[94:97]
	v_mfma_f32_16x16x32_bf16 v[82:85], v[206:209], v[190:193], v[82:85]
	v_mfma_f32_16x16x32_bf16 v[78:81], v[214:217], v[190:193], v[78:81]
	v_mfma_f32_16x16x32_bf16 v[74:77], v[206:209], v[198:201], v[74:77]
	v_mfma_f32_16x16x32_bf16 v[70:73], v[214:217], v[198:201], v[70:73]
	s_setprio 0
	s_mov_b32 m0, s31
	v_lshl_add_u64 v[218:219], s[50:51], 0, v[138:139]
	s_barrier
	ds_read_b128 v[170:173], v145 offset:16384
	ds_read_b128 v[174:177], v145 offset:17408
	ds_read_b128 v[178:181], v145 offset:18432
	ds_read_b128 v[182:185], v145 offset:19456
	ds_read_b128 v[186:189], v145 offset:20480
	ds_read_b128 v[190:193], v145 offset:21504
	ds_read_b128 v[194:197], v145 offset:22528
	ds_read_b128 v[198:201], v145 offset:23552
	global_load_lds_dwordx4 v[218:219], off
	v_lshl_add_u64 v[220:221], s[50:51], 0, v[134:135]
	s_mov_b32 m0, s58
	s_nop 0
	global_load_lds_dwordx4 v[220:221], off
	s_barrier
	s_waitcnt lgkmcnt(0)
	s_setprio 1
	s_waitcnt lgkmcnt(0)
	v_mfma_f32_16x16x32_bf16 v[66:69], v[146:149], v[170:173], v[66:69]
	v_mfma_f32_16x16x32_bf16 v[62:65], v[162:165], v[170:173], v[62:65]
	v_mfma_f32_16x16x32_bf16 v[58:61], v[146:149], v[178:181], v[58:61]
	v_mfma_f32_16x16x32_bf16 v[54:57], v[162:165], v[178:181], v[54:57]
	v_mfma_f32_16x16x32_bf16 v[42:45], v[146:149], v[186:189], v[42:45]
	v_mfma_f32_16x16x32_bf16 v[38:41], v[162:165], v[186:189], v[38:41]
	v_mfma_f32_16x16x32_bf16 v[22:25], v[146:149], v[194:197], v[22:25]
	v_mfma_f32_16x16x32_bf16 v[18:21], v[162:165], v[194:197], v[18:21]
	v_mfma_f32_16x16x32_bf16 v[66:69], v[150:153], v[174:177], v[66:69]
	v_mfma_f32_16x16x32_bf16 v[62:65], v[166:169], v[174:177], v[62:65]
	v_mfma_f32_16x16x32_bf16 v[58:61], v[150:153], v[182:185], v[58:61]
	v_mfma_f32_16x16x32_bf16 v[54:57], v[166:169], v[182:185], v[54:57]
	v_mfma_f32_16x16x32_bf16 v[42:45], v[150:153], v[190:193], v[42:45]
	v_mfma_f32_16x16x32_bf16 v[38:41], v[166:169], v[190:193], v[38:41]
	v_mfma_f32_16x16x32_bf16 v[22:25], v[150:153], v[198:201], v[22:25]
	v_mfma_f32_16x16x32_bf16 v[18:21], v[166:169], v[198:201], v[18:21]
	s_setprio 0
	s_barrier
; #define PG8_STAGE(bufoff, gbase, voff) do { _Pragma("unroll") for (int _i = 0; _i < 2; ++_i) \
;         __builtin_amdgcn_global_load_lds((const unsigned*)((const char*)(gbase) + (voff)[_i]), (LAS unsigned*)(lds + (bufoff) + ldsw + _i * 8192), 16, 0, 0); } while (0)
; #define PG8_LDA(dst, b, h) do { _Pragma("unroll") for (int m = 0; m < 4; ++m) _Pragma("unroll") for (int k = 0; k < 2; ++k) dst[m][k] = *(const LAS bf16x8*)(lds + PG8_SA(b, h) + aoff + m * 2048 + k * 1024); } while (0)
; #define PG8_LDB(dst, b, h) do { _Pragma("unroll") for (int n = 0; n < 2; ++n) _Pragma("unroll") for (int k = 0; k < 2; ++k) dst[n][k] = *(const LAS bf16x8*)(lds + PG8_SB(b, h) + boff + n * 2048 + k * 1024); } while (0)
; #define PG8_MMA(ai, bj, At, Bt) do { __builtin_amdgcn_s_setprio(1); _Pragma("unroll") for (int m = 0; m < 4; ++m) _Pragma("unroll") for (int n = 0; n < 2; ++n) _Pragma("unroll") for (int k = 0; k < 2; ++k) \
;         acc[ai][bj][m][n] = __builtin_amdgcn_mfma_f32_16x16x32_bf16(Bt[n][k], At[m][k], acc[ai][bj][m][n], 0, 0, 0); __builtin_amdgcn_s_setprio(0); } while (0)
; #define PG8_WAIT_V(n) asm volatile("s_waitcnt vmcnt(" #n ")" ::: "memory")
; #define PG8_WAIT_L(n) asm volatile("s_waitcnt lgkmcnt(" #n ")" ::: "memory")
; #define PG8_BAR __builtin_amdgcn_s_barrier()
; #define PG8_SCHED __builtin_amdgcn_sched_barrier(0)
; template <class Epi, class Sched>
; DI void gemm_phase(ldsp lds, const Gemm g, const Sched& S, const Epi& E, const int tid) {
;     ...
;             PG8_STAGE(PG8_SB(0, 1), b2 + hstep, voffB);
;             PG8_WAIT_V(6); PG8_BAR; PG8_MMA(1, 1, At, B1); PG8_BAR;
;             PG8_LDB(B0, 1, 0); PG8_SCHED; PG8_LDA(At, 1, 0); PG8_STAGE(PG8_SA(0, 1), a2 + hstep, voffA);
;             PG8_WAIT_L(8); PG8_BAR; PG8_WAIT_L(0); PG8_MMA(0, 0, At, B0); PG8_BAR; PG8_SCHED;
;             PG8_LDB(B1, 1, 1); PG8_STAGE(PG8_SB(1, 0), b3, voffB);
;             PG8_BAR; PG8_WAIT_L(0); PG8_MMA(0, 1, At, B1); PG8_BAR;
;             PG8_LDA(At, 1, 1); PG8_STAGE(PG8_SA(1, 0), a3, voffA);
;             PG8_BAR; PG8_WAIT_L(0); PG8_MMA(1, 0, At, B0); PG8_BAR; PG8_SCHED;
	s_add_u32 s72, s48, 0x40000
	s_addc_u32 s73, s49, 0
	s_add_i32 s74, s74, s35
	v_lshl_add_u64 v[146:147], s[72:73], 0, v[136:137]
	s_mov_b32 m0, s74
	s_nop 0
	global_load_lds_dwordx4 v[146:147], off
	v_lshl_add_u64 v[146:147], s[72:73], 0, v[30:31]
	s_add_i32 m0, s74, 0x2000
	s_nop 0
	global_load_lds_dwordx4 v[146:147], off
	s_waitcnt vmcnt(6)
	s_barrier
	s_setprio 1
	v_mfma_f32_16x16x32_bf16 v[50:53], v[202:205], v[170:173], v[50:53]
	v_mfma_f32_16x16x32_bf16 v[46:49], v[210:213], v[170:173], v[46:49]
	v_mfma_f32_16x16x32_bf16 v[34:37], v[202:205], v[178:181], v[34:37]
	v_mfma_f32_16x16x32_bf16 v[26:29], v[210:213], v[178:181], v[26:29]
	v_mfma_f32_16x16x32_bf16 v[14:17], v[202:205], v[186:189], v[14:17]
	v_mfma_f32_16x16x32_bf16 v[8:11], v[210:213], v[186:189], v[8:11]
	v_mfma_f32_16x16x32_bf16 v[4:7], v[202:205], v[194:197], v[4:7]
	v_mfma_f32_16x16x32_bf16 v[0:3], v[210:213], v[194:197], v[0:3]
	v_mfma_f32_16x16x32_bf16 v[50:53], v[206:209], v[174:177], v[50:53]
	v_mfma_f32_16x16x32_bf16 v[46:49], v[214:217], v[174:177], v[46:49]
	v_mfma_f32_16x16x32_bf16 v[34:37], v[206:209], v[182:185], v[34:37]
	v_mfma_f32_16x16x32_bf16 v[26:29], v[214:217], v[182:185], v[26:29]
	v_mfma_f32_16x16x32_bf16 v[14:17], v[206:209], v[190:193], v[14:17]
	v_mfma_f32_16x16x32_bf16 v[8:11], v[214:217], v[190:193], v[8:11]
	v_mfma_f32_16x16x32_bf16 v[4:7], v[206:209], v[198:201], v[4:7]
	v_mfma_f32_16x16x32_bf16 v[0:3], v[214:217], v[198:201], v[0:3]
	s_setprio 0
	s_add_i32 s72, 0, 0x18000
	v_add_u32_e32 v156, s72, v33
	s_barrier
	ds_read_b128 v[146:149], v156
	ds_read_b128 v[150:153], v156 offset:1024
	ds_read_b128 v[162:165], v156 offset:2048
	ds_read_b128 v[166:169], v156 offset:3072
	s_add_u32 s50, s50, 0x40000
	s_addc_u32 s51, s51, 0
	s_mov_b32 m0, s59
	v_lshl_add_u64 v[202:203], s[50:51], 0, v[138:139]
	ds_read_b128 v[170:173], v145 offset:32768
	ds_read_b128 v[174:177], v145 offset:33792
	ds_read_b128 v[178:181], v145 offset:34816
	ds_read_b128 v[182:185], v145 offset:35840
	ds_read_b128 v[186:189], v145 offset:36864
	ds_read_b128 v[190:193], v145 offset:37888
	ds_read_b128 v[194:197], v145 offset:38912
	ds_read_b128 v[198:201], v145 offset:39936
	global_load_lds_dwordx4 v[202:203], off
	v_lshl_add_u64 v[202:203], s[50:51], 0, v[134:135]
	s_mov_b32 m0, s60
	s_nop 0
	global_load_lds_dwordx4 v[202:203], off
	s_waitcnt lgkmcnt(8)
	s_barrier
	s_waitcnt lgkmcnt(0)
	s_setprio 1
	s_waitcnt lgkmcnt(0)
	v_mfma_f32_16x16x32_bf16 v[130:133], v[146:149], v[170:173], v[130:133]
	v_mfma_f32_16x16x32_bf16 v[126:129], v[162:165], v[170:173], v[126:129]
	v_mfma_f32_16x16x32_bf16 v[122:125], v[146:149], v[178:181], v[122:125]
	v_mfma_f32_16x16x32_bf16 v[118:121], v[162:165], v[178:181], v[118:121]
	v_mfma_f32_16x16x32_bf16 v[106:109], v[146:149], v[186:189], v[106:109]
	v_mfma_f32_16x16x32_bf16 v[102:105], v[162:165], v[186:189], v[102:105]
	v_mfma_f32_16x16x32_bf16 v[90:93], v[146:149], v[194:197], v[90:93]
	v_mfma_f32_16x16x32_bf16 v[86:89], v[162:165], v[194:197], v[86:89]
	v_mfma_f32_16x16x32_bf16 v[130:133], v[150:153], v[174:177], v[130:133]
	v_mfma_f32_16x16x32_bf16 v[126:129], v[166:169], v[174:177], v[126:129]
	v_mfma_f32_16x16x32_bf16 v[122:125], v[150:153], v[182:185], v[122:125]
	v_mfma_f32_16x16x32_bf16 v[118:121], v[166:169], v[182:185], v[118:121]
	v_mfma_f32_16x16x32_bf16 v[106:109], v[150:153], v[190:193], v[106:109]
	v_mfma_f32_16x16x32_bf16 v[102:105], v[166:169], v[190:193], v[102:105]
	v_mfma_f32_16x16x32_bf16 v[90:93], v[150:153], v[198:201], v[90:93]
	v_mfma_f32_16x16x32_bf16 v[86:89], v[166:169], v[198:201], v[86:89]
	s_setprio 0
	s_barrier
	s_add_i32 s50, 0, 0x1c000
	s_add_i32 s51, s72, s35
	v_add_u32_e32 v156, s50, v33
	v_lshl_add_u64 v[158:159], v[158:159], 0, s[96:97]
	s_mov_b32 m0, s51
	ds_read_b128 v[202:205], v156
	ds_read_b128 v[206:209], v156 offset:1024
	ds_read_b128 v[210:213], v156 offset:2048
	ds_read_b128 v[214:217], v156 offset:3072
	global_load_lds_dwordx4 v[158:159], off
	v_lshl_add_u64 v[158:159], v[160:161], 0, s[96:97]
	s_add_i32 m0, s51, 0x2000
	s_nop 0
	global_load_lds_dwordx4 v[158:159], off
	s_barrier
	s_waitcnt lgkmcnt(0)
	s_setprio 1
	s_waitcnt lgkmcnt(0)
	v_mfma_f32_16x16x32_bf16 v[114:117], v[202:205], v[170:173], v[114:117]
	v_mfma_f32_16x16x32_bf16 v[110:113], v[210:213], v[170:173], v[110:113]
	v_mfma_f32_16x16x32_bf16 v[98:101], v[202:205], v[178:181], v[98:101]
	v_mfma_f32_16x16x32_bf16 v[94:97], v[210:213], v[178:181], v[94:97]
	v_mfma_f32_16x16x32_bf16 v[82:85], v[202:205], v[186:189], v[82:85]
	v_mfma_f32_16x16x32_bf16 v[78:81], v[210:213], v[186:189], v[78:81]
	v_mfma_f32_16x16x32_bf16 v[74:77], v[202:205], v[194:197], v[74:77]
	v_mfma_f32_16x16x32_bf16 v[70:73], v[210:213], v[194:197], v[70:73]
	v_mfma_f32_16x16x32_bf16 v[114:117], v[206:209], v[174:177], v[114:117]
	v_mfma_f32_16x16x32_bf16 v[110:113], v[214:217], v[174:177], v[110:113]
	v_mfma_f32_16x16x32_bf16 v[98:101], v[206:209], v[182:185], v[98:101]
	v_mfma_f32_16x16x32_bf16 v[94:97], v[214:217], v[182:185], v[94:97]
	v_mfma_f32_16x16x32_bf16 v[82:85], v[206:209], v[190:193], v[82:85]
	v_mfma_f32_16x16x32_bf16 v[78:81], v[214:217], v[190:193], v[78:81]
	v_mfma_f32_16x16x32_bf16 v[74:77], v[206:209], v[198:201], v[74:77]
	v_mfma_f32_16x16x32_bf16 v[70:73], v[214:217], v[198:201], v[70:73]
	s_setprio 0
	s_mov_b32 m0, s62
	v_lshl_add_u64 v[158:159], v[218:219], 0, s[96:97]
	s_barrier
	ds_read_b128 v[170:173], v145 offset:49152
	ds_read_b128 v[174:177], v145 offset:50176
	ds_read_b128 v[178:181], v145 offset:51200
	ds_read_b128 v[182:185], v145 offset:52224
	ds_read_b128 v[186:189], v145 offset:53248
	ds_read_b128 v[190:193], v145 offset:54272
	ds_read_b128 v[194:197], v145 offset:55296
	ds_read_b128 v[198:201], v145 offset:56320
	global_load_lds_dwordx4 v[158:159], off
	v_lshl_add_u64 v[158:159], v[220:221], 0, s[96:97]
	s_mov_b32 m0, s63
	s_nop 0
	global_load_lds_dwordx4 v[158:159], off
	s_barrier
; DI unsigned cvt_pk_bf16(float lo, float hi) { const f32x2_t v = {lo, hi}; const bf16v2_t b = __builtin_convertvector(v, bf16v2_t); return __builtin_bit_cast(unsigned, b); }
; #define PG8_STAGE(bufoff, gbase, voff) do { _Pragma("unroll") for (int _i = 0; _i < 2; ++_i) \
;         __builtin_amdgcn_global_load_lds((const unsigned*)((const char*)(gbase) + (voff)[_i]), (LAS unsigned*)(lds + (bufoff) + ldsw + _i * 8192), 16, 0, 0); } while (0)
; #define PG8_MMA(ai, bj, At, Bt) do { __builtin_amdgcn_s_setprio(1); _Pragma("unroll") for (int m = 0; m < 4; ++m) _Pragma("unroll") for (int n = 0; n < 2; ++n) _Pragma("unroll") for (int k = 0; k < 2; ++k) \
;         acc[ai][bj][m][n] = __builtin_amdgcn_mfma_f32_16x16x32_bf16(Bt[n][k], At[m][k], acc[ai][bj][m][n], 0, 0, 0); __builtin_amdgcn_s_setprio(0); } while (0)
; #define PG8_WAIT_V(n) asm volatile("s_waitcnt vmcnt(" #n ")" ::: "memory")
; #define PG8_WAIT_L(n) asm volatile("s_waitcnt lgkmcnt(" #n ")" ::: "memory")
; #define PG8_BAR __builtin_amdgcn_s_barrier()
; #define PG8_SCHED __builtin_amdgcn_sched_barrier(0)
;     DI void operator()(const f32x4 (&acc)[2][2][4][2], const Unit& u, int wr, int wc, int fr, int fq) const {
;         const int row0 = u.pm * BM + wr * 64 + fr; const int col0 = u.pn * BM + wc * 32 + 8 * fq;
; #pragma unroll
;         for (int ai = 0; ai < 2; ++ai)
; #pragma unroll
;             for (int m = 0; m < 4; ++m) { const int row = row0 + ai * HALF + m * 16; bf16_t* rowp = O + (size_t)row * ldc + col0;
; #pragma unroll
;                 for (int bj = 0; bj < 2; ++bj) { const f32x4 v0 = acc[ai][bj][m][0], v1 = acc[ai][bj][m][1];
;                     u32x4 w; w.x = cvt_pk_bf16(v0[0], v0[1]); w.y = cvt_pk_bf16(v0[2], v0[3]); w.z = cvt_pk_bf16(v1[0], v1[1]); w.w = cvt_pk_bf16(v1[2], v1[3]);
;                     *(u32x4*)(rowp + bj * HALF) = w; } }
; template <class Epi, class Sched>
; DI void gemm_phase(ldsp lds, const Gemm g, const Sched& S, const Epi& E, const int tid) {
;     ...
;             PG8_BAR; PG8_WAIT_L(0); PG8_MMA(1, 0, At, B0); PG8_BAR; PG8_SCHED;
;             PG8_STAGE(PG8_SB(1, 1), b3 + hstep, voffB);
;             PG8_WAIT_V(6); PG8_BAR; PG8_MMA(1, 1, At, B1); PG8_BAR;
;         }
;         E(acc, cur, wr, wc, fr, fq);
	s_waitcnt lgkmcnt(0)
	s_setprio 1
	s_waitcnt lgkmcnt(0)
	v_mfma_f32_16x16x32_bf16 v[66:69], v[146:149], v[170:173], v[66:69]
	v_mfma_f32_16x16x32_bf16 v[62:65], v[162:165], v[170:173], v[62:65]
	v_mfma_f32_16x16x32_bf16 v[58:61], v[146:149], v[178:181], v[58:61]
	v_mfma_f32_16x16x32_bf16 v[54:57], v[162:165], v[178:181], v[54:57]
	v_mfma_f32_16x16x32_bf16 v[42:45], v[146:149], v[186:189], v[42:45]
	v_mfma_f32_16x16x32_bf16 v[38:41], v[162:165], v[186:189], v[38:41]
	v_mfma_f32_16x16x32_bf16 v[22:25], v[146:149], v[194:197], v[22:25]
	v_mfma_f32_16x16x32_bf16 v[18:21], v[162:165], v[194:197], v[18:21]
	v_mfma_f32_16x16x32_bf16 v[66:69], v[150:153], v[174:177], v[66:69]
	v_mfma_f32_16x16x32_bf16 v[62:65], v[166:169], v[174:177], v[62:65]
	v_mfma_f32_16x16x32_bf16 v[58:61], v[150:153], v[182:185], v[58:61]
	v_mfma_f32_16x16x32_bf16 v[54:57], v[166:169], v[182:185], v[54:57]
	v_mfma_f32_16x16x32_bf16 v[42:45], v[150:153], v[190:193], v[42:45]
	v_mfma_f32_16x16x32_bf16 v[38:41], v[166:169], v[190:193], v[38:41]
	v_mfma_f32_16x16x32_bf16 v[22:25], v[150:153], v[198:201], v[22:25]
	v_mfma_f32_16x16x32_bf16 v[18:21], v[166:169], v[198:201], v[18:21]
	s_setprio 0
	s_barrier
	s_add_u32 s48, s48, 0x40080
	s_addc_u32 s49, s49, 0
	s_add_i32 s50, s50, s35
	v_lshl_add_u64 v[146:147], s[48:49], 0, v[136:137]
	s_mov_b32 m0, s50
	s_nop 0
	global_load_lds_dwordx4 v[146:147], off
	v_lshl_add_u64 v[146:147], s[48:49], 0, v[30:31]
	s_add_i32 m0, s50, 0x2000
	s_nop 0
	global_load_lds_dwordx4 v[146:147], off
	s_waitcnt vmcnt(6)
	s_barrier
	s_setprio 1
	v_mfma_f32_16x16x32_bf16 v[50:53], v[202:205], v[170:173], v[50:53]
	v_mfma_f32_16x16x32_bf16 v[46:49], v[210:213], v[170:173], v[46:49]
	v_mfma_f32_16x16x32_bf16 v[34:37], v[202:205], v[178:181], v[34:37]
	v_mfma_f32_16x16x32_bf16 v[26:29], v[210:213], v[178:181], v[26:29]
	v_mfma_f32_16x16x32_bf16 v[14:17], v[202:205], v[186:189], v[14:17]
	v_mfma_f32_16x16x32_bf16 v[8:11], v[210:213], v[186:189], v[8:11]
	v_mfma_f32_16x16x32_bf16 v[4:7], v[202:205], v[194:197], v[4:7]
	v_mfma_f32_16x16x32_bf16 v[0:3], v[210:213], v[194:197], v[0:3]
	v_mfma_f32_16x16x32_bf16 v[50:53], v[206:209], v[174:177], v[50:53]
	v_mfma_f32_16x16x32_bf16 v[46:49], v[214:217], v[174:177], v[46:49]
	v_mfma_f32_16x16x32_bf16 v[34:37], v[206:209], v[182:185], v[34:37]
	v_mfma_f32_16x16x32_bf16 v[26:29], v[214:217], v[182:185], v[26:29]
	v_mfma_f32_16x16x32_bf16 v[14:17], v[206:209], v[190:193], v[14:17]
	v_mfma_f32_16x16x32_bf16 v[8:11], v[214:217], v[190:193], v[8:11]
	v_mfma_f32_16x16x32_bf16 v[4:7], v[206:209], v[198:201], v[4:7]
	v_mfma_f32_16x16x32_bf16 v[0:3], v[214:217], v[198:201], v[0:3]
	s_setprio 0
	s_add_i32 s69, s69, 2
	s_add_u32 s46, s46, 0x100
	s_addc_u32 s47, s47, 0
	s_add_u32 s67, s67, 0x100
	s_addc_u32 s68, s68, 0
	s_cmp_gt_u32 s69, 13
	s_barrier
	s_cbranch_scc0 .LBB0_663
	s_lshl_b32 s101, s30, 8
	s_mul_i32 s101, s101, s14
	s_lshl_b32 s99, s64, 8
	s_add_u32 s101, s101, s99
	s_lshl_b32 s101, s101, 1
	s_add_u32 s98, s26, s101
	s_addc_u32 s99, s27, 0
	v_cvt_pk_bf16_f32 v114, v114, v115
	v_cvt_pk_bf16_f32 v115, v116, v117
	v_cvt_pk_bf16_f32 v116, v110, v111
	v_cvt_pk_bf16_f32 v117, v112, v113
	global_store_dwordx4 v224, v[114:117], s[98:99] offset:256
	v_cvt_pk_bf16_f32 v130, v130, v131
	v_cvt_pk_bf16_f32 v131, v132, v133
	v_cvt_pk_bf16_f32 v132, v126, v127
	v_cvt_pk_bf16_f32 v133, v128, v129
	global_store_dwordx4 v224, v[130:133], s[98:99]
	s_mul_i32 s101, s100, 1
	v_add_u32_e32 v226, s101, v224
	v_cvt_pk_bf16_f32 v98, v98, v99
	v_cvt_pk_bf16_f32 v99, v100, v101
	v_cvt_pk_bf16_f32 v100, v94, v95
	v_cvt_pk_bf16_f32 v101, v96, v97
	global_store_dwordx4 v226, v[98:101], s[98:99] offset:256
	v_cvt_pk_bf16_f32 v122, v122, v123
	v_cvt_pk_bf16_f32 v123, v124, v125
	v_cvt_pk_bf16_f32 v124, v118, v119
	v_cvt_pk_bf16_f32 v125, v120, v121
	global_store_dwordx4 v226, v[122:125], s[98:99]
	s_mul_i32 s101, s100, 2
	v_add_u32_e32 v225, s101, v224
	v_cvt_pk_bf16_f32 v82, v82, v83
	v_cvt_pk_bf16_f32 v83, v84, v85
	v_cvt_pk_bf16_f32 v84, v78, v79
	v_cvt_pk_bf16_f32 v85, v80, v81
	global_store_dwordx4 v225, v[82:85], s[98:99] offset:256
	v_cvt_pk_bf16_f32 v106, v106, v107
	v_cvt_pk_bf16_f32 v107, v108, v109
	v_cvt_pk_bf16_f32 v108, v102, v103
	v_cvt_pk_bf16_f32 v109, v104, v105
	global_store_dwordx4 v225, v[106:109], s[98:99]
	s_mul_i32 s101, s100, 3
	v_add_u32_e32 v226, s101, v224
	v_cvt_pk_bf16_f32 v74, v74, v75
	v_cvt_pk_bf16_f32 v75, v76, v77
	v_cvt_pk_bf16_f32 v76, v70, v71
	v_cvt_pk_bf16_f32 v77, v72, v73
	global_store_dwordx4 v226, v[74:77], s[98:99] offset:256
	v_cvt_pk_bf16_f32 v90, v90, v91
	v_cvt_pk_bf16_f32 v91, v92, v93
	v_cvt_pk_bf16_f32 v92, v86, v87
	v_cvt_pk_bf16_f32 v93, v88, v89
	global_store_dwordx4 v226, v[90:93], s[98:99]
	s_mul_i32 s101, s100, 8
	v_add_u32_e32 v225, s101, v224
	v_cvt_pk_bf16_f32 v50, v50, v51
	v_cvt_pk_bf16_f32 v51, v52, v53
	v_cvt_pk_bf16_f32 v52, v46, v47
	v_cvt_pk_bf16_f32 v53, v48, v49
	global_store_dwordx4 v225, v[50:53], s[98:99] offset:256
	v_cvt_pk_bf16_f32 v66, v66, v67
	v_cvt_pk_bf16_f32 v67, v68, v69
	v_cvt_pk_bf16_f32 v68, v62, v63
	v_cvt_pk_bf16_f32 v69, v64, v65
	global_store_dwordx4 v225, v[66:69], s[98:99]
	s_mul_i32 s101, s100, 9
	v_add_u32_e32 v226, s101, v224
	v_cvt_pk_bf16_f32 v34, v34, v35
	v_cvt_pk_bf16_f32 v35, v36, v37
	v_cvt_pk_bf16_f32 v36, v26, v27
	v_cvt_pk_bf16_f32 v37, v28, v29
	global_store_dwordx4 v226, v[34:37], s[98:99] offset:256
	v_cvt_pk_bf16_f32 v58, v58, v59
	v_cvt_pk_bf16_f32 v59, v60, v61
	v_cvt_pk_bf16_f32 v60, v54, v55
	v_cvt_pk_bf16_f32 v61, v56, v57
	global_store_dwordx4 v226, v[58:61], s[98:99]
	s_mul_i32 s101, s100, 10
	v_add_u32_e32 v225, s101, v224
	v_cvt_pk_bf16_f32 v14, v14, v15
	v_cvt_pk_bf16_f32 v15, v16, v17
	v_cvt_pk_bf16_f32 v16, v8, v9
	v_cvt_pk_bf16_f32 v17, v10, v11
	global_store_dwordx4 v225, v[14:17], s[98:99] offset:256
	v_cvt_pk_bf16_f32 v42, v42, v43
	v_cvt_pk_bf16_f32 v43, v44, v45
	v_cvt_pk_bf16_f32 v44, v38, v39
	v_cvt_pk_bf16_f32 v45, v40, v41
	global_store_dwordx4 v225, v[42:45], s[98:99]
	s_mul_i32 s101, s100, 11
	v_add_u32_e32 v226, s101, v224
	v_cvt_pk_bf16_f32 v4, v4, v5
	v_cvt_pk_bf16_f32 v5, v6, v7
	v_cvt_pk_bf16_f32 v6, v0, v1
	v_cvt_pk_bf16_f32 v7, v2, v3
	global_store_dwordx4 v226, v[4:7], s[98:99] offset:256
	v_cvt_pk_bf16_f32 v22, v22, v23
	v_cvt_pk_bf16_f32 v23, v24, v25
	v_cvt_pk_bf16_f32 v24, v18, v19
	v_cvt_pk_bf16_f32 v25, v20, v21
	global_store_dwordx4 v226, v[22:25], s[98:99]
	s_and_b64 vcc, exec, s[38:39]
	s_mov_b32 s64, s36
	s_mov_b32 s30, s40
	s_mov_b64 s[48:49], s[44:45]
	s_mov_b64 s[46:47], s[42:43]
	v_readlane_b32 s78, v254, 54
	s_cbranch_vccz .LBB0_660
	s_waitcnt vmcnt(0)
	v_readlane_b32 s72, v254, 58
	s_cmpk_gt_u32 s15, 0xff
	v_readlane_b32 s73, v254, 59
	s_cbranch_scc1 .LBB0_667
	s_barrier

; __global__ void __launch_bounds__(NTHREADS, 2) megak(Params p) {
;     extern __shared__ __attribute__((aligned(16))) unsigned char shm[];
	.amdhsa_kernel _Z5megak6Params
		.amdhsa_group_segment_fixed_size 0
		.amdhsa_private_segment_fixed_size 0
		.amdhsa_kernarg_size 376
		.amdhsa_user_sgpr_count 2
		.amdhsa_user_sgpr_dispatch_ptr 0
		.amdhsa_user_sgpr_queue_ptr 0
		.amdhsa_user_sgpr_kernarg_segment_ptr 1
		.amdhsa_user_sgpr_dispatch_id 0
		.amdhsa_user_sgpr_kernarg_preload_length 0
		.amdhsa_user_sgpr_kernarg_preload_offset 0
		.amdhsa_user_sgpr_private_segment_size 0
		.amdhsa_uses_dynamic_stack 0
		.amdhsa_enable_private_segment 0
		.amdhsa_system_sgpr_workgroup_id_x 1
		.amdhsa_system_sgpr_workgroup_id_y 0
		.amdhsa_system_sgpr_workgroup_id_z 0
		.amdhsa_system_sgpr_workgroup_info 0
		.amdhsa_system_vgpr_workitem_id 2
		.amdhsa_next_free_vgpr 256
		.amdhsa_next_free_sgpr 102
		.amdhsa_accum_offset 256
		.amdhsa_reserve_vcc 1
		.amdhsa_float_round_mode_32 0
		.amdhsa_float_round_mode_16_64 0
		.amdhsa_float_denorm_mode_32 3
		.amdhsa_float_denorm_mode_16_64 3
		.amdhsa_dx10_clamp 1
		.amdhsa_ieee_mode 1
		.amdhsa_fp16_overflow 0
		.amdhsa_tg_split 0
		.amdhsa_exception_fp_ieee_invalid_op 0
		.amdhsa_exception_fp_denorm_src 0
		.amdhsa_exception_fp_ieee_div_zero 0
		.amdhsa_exception_fp_ieee_overflow 0
		.amdhsa_exception_fp_ieee_underflow 0
		.amdhsa_exception_fp_ieee_inexact 0
		.amdhsa_exception_int_div_zero 0
	.end_amdhsa_kernel

; __global__ void __launch_bounds__(NTHREADS, 2) megak(Params p) {
;     extern __shared__ __attribute__((aligned(16))) unsigned char shm[];
amdhsa.kernels:
  - .agpr_count:     0
    .args:
      - .offset:         0
        .size:           120
        .value_kind:     by_value
      - .offset:         120
        .size:           4
        .value_kind:     hidden_block_count_x
      - .offset:         124
        .size:           4
        .value_kind:     hidden_block_count_y
      - .offset:         128
        .size:           4
        .value_kind:     hidden_block_count_z
      - .offset:         132
        .size:           2
        .value_kind:     hidden_group_size_x
      - .offset:         134
        .size:           2
        .value_kind:     hidden_group_size_y
      - .offset:         136
        .size:           2
        .value_kind:     hidden_group_size_z
      - .offset:         138
        .size:           2
        .value_kind:     hidden_remainder_x
      - .offset:         140
        .size:           2
        .value_kind:     hidden_remainder_y
      - .offset:         142
        .size:           2
        .value_kind:     hidden_remainder_z
      - .offset:         160
        .size:           8
        .value_kind:     hidden_global_offset_x
      - .offset:         168
        .size:           8
        .value_kind:     hidden_global_offset_y
      - .offset:         176
        .size:           8
        .value_kind:     hidden_global_offset_z
      - .offset:         184
        .size:           2
        .value_kind:     hidden_grid_dims
      - .offset:         208
        .size:           8
        .value_kind:     hidden_multigrid_sync_arg
      - .offset:         240
        .size:           4
        .value_kind:     hidden_dynamic_lds_size
    .group_segment_fixed_size: 0
    .kernarg_segment_align: 8
    .kernarg_segment_size: 376
    .language:       OpenCL C
    .language_version:
      - 2
      - 0
    .max_flat_workgroup_size: 512
    .name:           _Z5megak6Params
    .private_segment_fixed_size: 0
    .sgpr_count:     108
    .sgpr_spill_count: 286
    .symbol:         _Z5megak6Params.kd
    .uniform_work_group_size: 1
    .uses_dynamic_stack: false
    .vgpr_count:     256
    .vgpr_spill_count: 0
    .wavefront_size: 64
